# v42 + priority swapped inside the scan loop (waves 0-3 raised while scanning, waves 4-7 elsewhere)
# speedup vs baseline: 1.0046x; 1.0024x over previous
.LBB0_537:
	s_or_b64 exec, exec, s[0:1]
	s_and_b64 s[0:1], s[36:37], exec
	s_cselect_b32 s28, 16, 0x1000
	s_add_u32 s64, s76, 0x13d00000
	s_addc_u32 s65, s77, 0
	s_bfe_u32 s68, s96, 0x20006
	s_mul_i32 s0, s68, 0x3700
	s_add_i32 s71, s0, 0
	s_and_b32 s0, s96, 0xffffff00
	s_lshr_b32 s74, s96, 8
	s_add_i32 s84, s0, 0
	s_lshl_b32 s11, s74, 5
	s_add_i32 s80, s84, 0x12600
	s_cmpk_lt_u32 s96, 0x540
	v_readlane_b32 s20, v255, 31
	s_cselect_b64 s[40:41], -1, 0
	s_add_i32 s12, s20, -4
	s_lshl_b32 s13, s12, 2
	s_lshl_b32 s22, s12, 10
	s_cmpk_lt_u32 s96, 0x440
	s_cselect_b64 s[42:43], -1, 0
	s_lshl_b32 s66, s20, 10
	s_cmpk_lt_u32 s96, 0x340
	s_cselect_b64 s[46:47], -1, 0
	s_add_i32 s14, s20, 4
	s_lshl_b32 s15, s14, 2
	s_lshl_b32 s23, s14, 10
	s_cmpk_lt_u32 s96, 0x240
	s_cselect_b64 s[48:49], -1, 0
	s_add_i32 s16, s20, 8
	s_lshl_b32 s17, s16, 2
	s_lshl_b32 s24, s16, 10
	s_cmp_eq_u32 s20, 4
	s_cselect_b64 s[50:51], -1, 0
	s_cmp_eq_u32 s20, 2
	s_mov_b32 s0, 0xfc00000
	s_cselect_b32 s38, s0, 0x13d00000
	s_add_u32 s8, s76, s6
	s_addc_u32 s9, s77, 0
	s_mul_i32 s0, s20, 0x2400
	s_add_i32 s1, 0, 0x1a900
	s_add_i32 s81, s1, s0
	s_lshl_b32 s0, s74, 7
	s_add_i32 s83, s0, 0
	s_add_i32 s82, s81, 0x2000
	s_add_i32 s83, s83, 0x14800
	s_add_i32 s84, s84, 0x12400
	s_lshl_b32 s29, s20, 5
	s_add_u32 s6, s64, s6
	s_addc_u32 s7, s65, 0
	s_lshl_b32 s85, s33, 10
	s_add_u32 s18, s76, 0x10000
	v_writelane_b32 v255, s96, 33
	s_addc_u32 s19, s77, 0
	v_lshl_or_b32 v11, s68, 4, v9
	v_writelane_b32 v255, s18, 34
	v_add_u32_e32 v25, 1, v11
	v_lshlrev_b32_e32 v27, 3, v38
	v_writelane_b32 v255, s19, 35
	v_lshlrev_b32_e32 v10, 7, v25
	v_and_b32_e32 v22, 8, v27
	s_add_i32 s0, 0, 0x1cd00
	s_add_i32 s18, 0, 0x1f100
	v_add3_u32 v91, s1, v10, v22
	v_add3_u32 v92, s0, v10, v22
	v_add3_u32 v93, s18, v10, v22
	v_lshlrev_b32_e32 v10, 8, v25
	s_add_i32 s19, 0, 0x23900
	v_add3_u32 v28, s19, v10, v22
	v_lshlrev_b32_e32 v10, 7, v11
	v_add3_u32 v94, s1, v10, v22
	v_add3_u32 v95, s0, v10, v22
	v_add3_u32 v96, s18, v10, v22
	v_lshlrev_b32_e32 v10, 8, v11
	v_add3_u32 v29, s19, v10, v22
	v_add_u32_e32 v10, 1, v89
	s_add_i32 s19, 0, 0x21500
	v_lshl_add_u32 v32, v10, 7, s19
	v_xor_b32_e32 v10, v10, v39
	v_lshlrev_b32_e32 v10, 4, v10
	v_and_b32_e32 v33, 0x70, v10
	v_lshlrev_b32_e32 v10, 7, v89
	v_add_u32_e32 v34, s19, v10
	s_add_i32 s19, 0, 0x12800
	s_cmp_lg_u32 s12, 16
	v_add_u32_e32 v36, s19, v10
	v_or_b32_e32 v10, s13, v38
	s_cselect_b64 vcc, -1, 0
	v_xor_b32_e32 v22, v89, v39
	v_cndmask_b32_e32 v98, 64, v10, vcc
	v_bitop3_b32 v10, v38, v39, s13 bitop3:0x36
	v_lshlrev_b32_e32 v22, 4, v22
	v_and_or_b32 v10, v10, 7, v41
	v_and_b32_e32 v35, 0x70, v22
	v_lshlrev_b32_e32 v22, 4, v10
	v_mov_b32_e32 v10, 0
	v_mov_b32_e32 v23, v10
	s_cmp_lg_u32 s20, 16
	v_lshl_add_u64 v[48:49], s[4:5], 0, v[22:23]
	v_or_b32_e32 v22, s3, v38
	s_cselect_b64 vcc, -1, 0
	v_cndmask_b32_e32 v99, 64, v22, vcc
	v_bitop3_b32 v22, v38, v39, s3 bitop3:0x36
	v_and_or_b32 v22, v22, 7, v41
	v_lshlrev_b32_e32 v22, 4, v22
	s_cmp_lg_u32 s14, 16
	v_lshl_add_u64 v[50:51], s[4:5], 0, v[22:23]
	v_or_b32_e32 v22, s15, v38
	s_cselect_b64 vcc, -1, 0
	v_cndmask_b32_e32 v100, 64, v22, vcc
	v_bitop3_b32 v22, v38, v39, s15 bitop3:0x36
	v_and_or_b32 v22, v22, 7, v41
	v_lshlrev_b32_e32 v22, 4, v22
	s_cmp_lg_u32 s16, 16
	v_lshl_add_u64 v[52:53], s[4:5], 0, v[22:23]
	v_or_b32_e32 v22, s17, v38
	s_cselect_b64 vcc, -1, 0
	v_cndmask_b32_e32 v101, 64, v22, vcc
	v_bitop3_b32 v22, v38, v39, s17 bitop3:0x36
	v_and_or_b32 v22, v22, 7, v41
	v_lshlrev_b32_e32 v22, 4, v22
	v_lshl_add_u64 v[54:55], s[4:5], 0, v[22:23]
	v_xor_b32_e32 v22, v38, v20
	s_movk_i32 s10, 0x3700
	v_or_b32_e32 v22, v22, v41
	v_lshlrev_b32_e32 v41, 5, v9
	v_lshrrev_b32_e32 v45, 7, v42
	v_cmp_gt_u32_e64 s[0:1], 16, v40
	v_or_b32_e32 v103, v27, v41
	v_lshl_add_u32 v104, v40, 2, s71
	v_add_u32_e32 v40, s71, v41
	v_lshrrev_b32_e32 v41, 2, v9
	v_mul_lo_u32 v45, v45, s10
	v_or_b32_e32 v41, v90, v41
	v_add_u32_e32 v67, 0, v45
	v_bfe_u32 v45, v42, 3, 4
	v_mul_u32_u24_e32 v41, 0x48, v41
	v_and_b32_e32 v21, 12, v21
	v_mul_u32_u24_e32 v45, 0x48, v45
	v_or_b32_e32 v24, s11, v90
	v_add_lshl_u32 v105, v21, v41, 1
	v_lshl_or_b32 v21, v89, 6, v8
	v_add_lshl_u32 v8, v45, v8, 1
	v_mov_b32_e32 v45, v10
	v_and_b32_e32 v26, 7, v25
	v_lshl_add_u64 v[60:61], s[6:7], 0, v[44:45]
	v_cmp_eq_u32_e64 s[6:7], 0, v42
	v_lshrrev_b32_e32 v42, 3, v24
	v_and_b32_e32 v62, 8, v42
	v_bitop3_b32 v63, v42, v26, 5 bitop3:0x6c
	v_or_b32_e32 v63, v63, v62
	v_lshlrev_b32_e32 v68, 4, v63
	v_add_u32_e32 v63, 64, v24
	v_bitop3_b32 v45, v42, v25, 7 bitop3:0x78
	v_lshrrev_b32_e32 v64, 3, v63
	v_xor_b32_e32 v69, v42, v20
	v_bitop3_b32 v42, v42, v20, 5 bitop3:0x6c
	v_and_b32_e32 v65, 8, v64
	v_or_b32_e32 v42, v42, v62
	v_bitop3_b32 v62, v64, v20, 5 bitop3:0x6c
	v_or_b32_e32 v62, v62, v65
	v_lshlrev_b32_e32 v108, 4, v69
	v_lshlrev_b32_e32 v69, 4, v62
	v_or_b32_e32 v62, 16, v24
	v_lshlrev_b32_e32 v22, 4, v22
	v_lshlrev_b32_e32 v71, 1, v63
	v_lshrrev_b32_e32 v63, 3, v62
	v_lshl_add_u64 v[56:57], s[4:5], 0, v[22:23]
	v_xor_b32_e32 v22, v88, v20
	v_bitop3_b32 v26, v64, v26, 5 bitop3:0x6c
	v_bitop3_b32 v64, v63, v25, 7 bitop3:0x78
	v_lshlrev_b32_e32 v22, 4, v22
	v_or_b32_e32 v26, v26, v65
	v_lshlrev_b32_e32 v111, 4, v64
	v_and_b32_e32 v64, 8, v63
	v_bitop3_b32 v65, v63, v25, 7 bitop3:0x28
	s_movk_i32 s18, 0x48
	v_lshl_add_u64 v[58:59], s[8:9], 0, v[22:23]
	v_or_b32_e32 v23, s11, v9
	v_or_b32_e32 v65, v65, v64
	v_mul_u32_u24_e32 v30, 0x48, v11
	v_mul_u32_u24_e32 v31, 0x48, v9
	v_lshlrev_b32_e32 v97, 2, v11
	v_or_b32_e32 v22, 16, v90
	v_lshlrev_b32_e32 v72, 4, v65
	v_add_u32_e32 v65, 0x50, v24
	v_mul_lo_u32 v23, v23, s18
	v_mad_u32_u24 v11, v11, s18, 32
	v_lshlrev_b32_e32 v70, 1, v24
	v_add_lshl_u32 v109, v24, v30, 1
	v_add_lshl_u32 v110, v24, v31, 1
	v_lshrrev_b32_e32 v73, 3, v65
	v_xor_b32_e32 v75, v63, v20
	v_bitop3_b32 v63, v63, v20, 7 bitop3:0x6c
	v_add_lshl_u32 v113, v62, v30, 1
	v_add_lshl_u32 v115, v30, v90, 1
	v_add_lshl_u32 v116, v22, v30, 1
	v_add_u32_e32 v30, 0x480, v23
	v_add_lshl_u32 v119, v11, v90, 1
	v_add_lshl_u32 v120, v11, v22, 1
	v_or_b32_e32 v11, 32, v90
	v_lshlrev_b32_e32 v123, 2, v24
	v_or_b32_e32 v24, 1, v90
	v_cmp_eq_u32_e32 vcc, v90, v9
	v_lshlrev_b32_e32 v106, 5, v20
	v_and_b32_e32 v74, 8, v73
	v_bitop3_b32 v25, v73, v25, 7 bitop3:0x28
	v_or_b32_e32 v63, v63, v64
	v_bitop3_b32 v20, v73, v20, 7 bitop3:0x6c
	v_lshlrev_b32_e32 v73, 1, v62
	v_add_lshl_u32 v114, v62, v31, 1
	v_add_lshl_u32 v118, v30, v90, 1
	v_add_lshl_u32 v122, v11, v30, 1
	v_lshlrev_b32_e32 v124, 2, v62
	v_or_b32_e32 v30, 2, v90
	v_cndmask_b32_e64 v62, 0, 1.0, vcc
	v_cmp_eq_u32_e32 vcc, v24, v9
	v_lshlrev_b32_e32 v112, 4, v75
	v_lshlrev_b32_e32 v75, 4, v63
	v_add_lshl_u32 v117, v90, v23, 1
	v_add_lshl_u32 v121, v11, v23, 1
	v_add_lshl_u32 v125, v90, v31, 1
	v_add_lshl_u32 v23, v11, v31, 1
	v_or_b32_e32 v31, 3, v90
	v_cndmask_b32_e64 v63, 0, 1.0, vcc
	v_cmp_eq_u32_e32 vcc, v30, v9
	v_cmp_eq_u32_e64 s[4:5], 0, v9
	v_mad_u32_u24 v37, v9, s18, 16
	v_cmp_lt_u32_e64 s[8:9], v90, v9
	v_cmp_gt_u32_e64 s[10:11], v90, v9
	v_cmp_lt_u32_e64 s[12:13], v24, v9
	v_cmp_lt_u32_e64 s[14:15], v30, v9
	v_cmp_gt_u32_e64 s[16:17], v30, v9
	v_cmp_lt_u32_e64 s[18:19], v31, v9
	v_cmp_gt_u32_e64 s[20:21], v31, v9
	v_cndmask_b32_e64 v64, 0, 1.0, vcc
	v_cmp_eq_u32_e32 vcc, v31, v9
	v_lshlrev_b32_e32 v9, 2, v9
	v_lshl_add_u32 v24, v38, 10, s97
	s_mov_b32 s3, 0xdc00
	v_add3_u32 v126, v24, v9, s3
	v_and_b32_e32 v9, 3, v39
	s_movk_i32 s25, 0x2400
	v_lshlrev_b32_e32 v43, 2, v21
	v_lshlrev_b32_e32 v21, 1, v21
	v_lshl_or_b32 v9, v9, 3, s29
	v_lshlrev_b32_e32 v24, 1, v41
	s_waitcnt lgkmcnt(0)
	s_barrier
	v_lshlrev_b32_e32 v66, 2, v89
	v_or_b32_e32 v25, v25, v74
	v_or_b32_e32 v20, v20, v74
	v_add3_u32 v128, v9, v24, s25
	v_mov_b32_e32 v9, 0x3540
	v_add_u32_e32 v151, v67, v8
	v_add_u32_e32 v8, 0, v21
	s_mov_b32 s39, 0
	v_and_b32_e32 v102, 48, v39
	v_lshlrev_b32_e32 v26, 4, v26
	v_lshlrev_b32_e32 v42, 4, v42
	v_lshlrev_b32_e32 v25, 4, v25
	v_lshlrev_b32_e32 v20, 4, v20
	v_lshlrev_b32_e32 v74, 1, v65
	v_add_lshl_u32 v22, v37, v90, 1
	v_add_lshl_u32 v11, v11, v37, 1
	v_writelane_b32 v255, s97, 32
	v_lshl_or_b32 v129, v38, 4, v9
	s_add_i32 s3, 0, 0x15c00
	s_add_i32 s88, s22, 0
	s_add_i32 s89, s23, 0
	s_add_i32 s90, s24, 0
	v_add_u32_e32 v9, 0, v66
	v_add_u32_e32 v152, 0x12800, v8
	v_mbcnt_lo_u32_b32 v8, -1, 0
	s_mov_b64 s[52:53], s[38:39]
	v_add_u32_e32 v107, s70, v89
	v_lshlrev_b32_e32 v45, 4, v45
	v_cndmask_b32_e64 v65, 0, 1.0, vcc
	v_add_u32_e32 v127, 0x2d00, v103
	v_writelane_b32 v255, s29, 44
	v_or_b32_e32 v130, 0x3500, v102
	v_add_u32_e32 v131, v28, v68
	v_add_u32_e32 v132, v28, v26
	v_add_u32_e32 v133, v29, v42
	v_add_u32_e32 v134, v29, v69
	v_add_u32_e32 v135, s3, v70
	v_add_u32_e32 v136, s3, v71
	s_mov_b32 s86, 0x4038aa3b
	s_add_i32 s67, 0, 0x10000
	v_add_u32_e32 v137, v28, v72
	v_add_u32_e32 v138, v28, v25
	v_add_u32_e32 v139, v29, v75
	v_add_u32_e32 v140, v29, v20
	v_add_u32_e32 v141, s3, v73
	v_add_u32_e32 v142, s3, v74
	v_add_u32_e32 v143, v32, v33
	v_add_u32_e32 v145, v34, v35
	s_mov_b32 s87, 0xbfb8aa3b
	v_add_u32_e32 v146, v36, v44
	s_add_i32 s88, s88, 0x23900
	s_add_i32 s89, s89, 0x23900
	s_add_i32 s90, s90, 0x23900
	s_add_i32 s91, 0, 0x27900
	s_add_i32 s92, s81, 0x400
	s_add_i32 s93, s81, 0x800
	s_add_i32 s94, s81, 0xc00
	s_add_i32 s95, s81, 0x1400
	s_add_i32 s96, s81, 0x1800
	s_add_i32 s97, s81, 0x1c00
	s_add_i32 s3, 0, 0x16100
	s_add_i32 s69, 0, 0x18500
	v_mov_b32_e32 v147, 0xbf92477c
	v_add_u32_e32 v148, v40, v27
	s_xor_b64 s[54:55], s[26:27], -1
	v_add_u32_e32 v149, 0, v43
	v_add_u32_e32 v150, 0x12400, v9
	v_mov_b32_e32 v153, 0x3a27c5ac
	v_mbcnt_hi_u32_b32 v144, -1, v8
	v_add_u32_e32 v154, s71, v22
	v_add_u32_e32 v155, s71, v23
	v_add_u32_e32 v156, s71, v11
	s_mov_b32 s33, s28
	s_mov_b32 s29, 0
	v_add_u32_e32 v211, v93, v45
	v_add_u32_e32 v233, s67, v119
	v_add_u32_e32 v210, v96, v108
	v_add_u32_e32 v224, s71, v114
	v_add_u32_e32 v228, s67, v116
	v_add_u32_e32 v232, s69, v118
	v_add_u32_e32 v214, s71, v110
	v_add_u32_e32 v223, s67, v113
	v_add_u32_e32 v212, v91, v45
	v_add_u32_e32 v213, s67, v109
	v_add_u32_e32 v239, 0x12600, v97
	v_add_u32_e32 v235, s3, v121
	v_add_u32_e32 v219, v93, v111
	v_add_u32_e32 v208, v94, v108
	v_add_u32_e32 v220, v91, v111
	v_xor_b32_e32 v243, 32, v144
	v_and_b32_e32 v241, 64, v144
	v_add_u32_e32 v21, 64, v241
	v_cmp_lt_i32_e32 vcc, v243, v21
	s_nop 1
	v_cndmask_b32_e32 v20, v144, v243, vcc
	v_lshlrev_b32_e32 v222, 2, v20
	v_xor_b32_e32 v242, 16, v144
	v_cmp_lt_i32_e32 vcc, v242, v21
	s_nop 1
	v_cndmask_b32_e32 v22, v144, v242, vcc
	v_lshlrev_b32_e32 v221, 2, v22
	v_add_u32_e32 v237, s3, v122
	v_add_u32_e32 v231, s3, v118
	v_add_u32_e32 v207, v92, v45
	v_or_b32_e32 v240, v102, v241
	v_add_u32_e32 v217, v95, v112
	v_add_u32_e32 v215, v92, v111
	v_add_u32_e32 v227, s67, v115
	v_add_u32_e32 v236, s69, v121
	v_add_u32_e32 v225, 0x15d80, v44
	v_add_u32_e32 v209, v95, v108
	v_add_u32_e32 v230, s69, v117
	v_add_u32_e32 v218, v96, v112
	v_add_u32_e32 v226, s83, v102
	v_add_u32_e32 v229, s3, v117
	v_add_u32_e32 v216, v94, v112
	v_add_u32_e32 v238, s69, v122
	v_add_u32_e32 v234, s67, v120
	v_mov_b32_e32 v252, 0
	s_waitcnt vmcnt(0)
	v_readlane_b32 vcc_lo, v255, 33
	s_nop 3
	s_cmp_ge_u32 vcc_lo, 0x100
	s_cbranch_scc1 .Lsp_hi
	s_setprio 1
	s_branch .Lsp_done
.Lsp_hi:
	s_setprio 0
.Lsp_done:
.LBB0_538:
	s_sub_i32 s22, s28, s29
	s_min_u32 s24, s22, 64
	s_lshr_b32 s22, s24, 4
	s_cmp_lt_u32 s68, s22
	s_cselect_b64 s[34:35], -1, 0
	s_cmp_ge_u32 s68, s22
	s_cbranch_scc1 .LBB0_542
	ds_read_b64 v[24:25], v207
	ds_read_b64 v[34:35], v132
	ds_read_b64 v[8:9], v208
	ds_read_b64 v[26:27], v209
	ds_read_b64 v[36:37], v210
	ds_read2_b64 v[20:23], v135 offset1:32
	ds_read_b64 v[38:39], v134
	ds_read_b64 v[28:29], v136
	ds_read_b64 v[40:41], v211
	ds_read_b64 v[42:43], v131
	ds_read_b64 v[32:33], v212
	s_waitcnt lgkmcnt(7)
	v_pk_add_f16 v11, v26, v24 neg_lo:[0,1] neg_hi:[0,1]
	v_pk_add_f16 v26, v27, v25 neg_lo:[0,1] neg_hi:[0,1]
	s_waitcnt lgkmcnt(3)
	v_pk_fma_f16 v66, v11, v28, v24
	v_pk_fma_f16 v67, v26, v29, v25
	ds_read_b64 v[68:69], v133
	ds_read2_b64 v[28:31], v135 offset0:96 offset1:112
	s_waitcnt lgkmcnt(4)
	v_pk_add_f16 v11, v36, v40 neg_lo:[0,1] neg_hi:[0,1]
	v_pk_add_f16 v70, v37, v41 neg_lo:[0,1] neg_hi:[0,1]
	v_pk_add_f16 v38, v38, v34 neg_lo:[0,1] neg_hi:[0,1]
	s_waitcnt lgkmcnt(1)
	v_pk_add_f16 v24, v68, v42 neg_lo:[0,1] neg_hi:[0,1]
	v_pk_add_f16 v25, v69, v43 neg_lo:[0,1] neg_hi:[0,1]
	s_waitcnt lgkmcnt(0)
	v_pk_fma_f16 v24, v24, v28, v42
	v_pk_fma_f16 v25, v25, v29, v43
	v_fma_mix_f32 v36, v24, s86, 0 op_sel_hi:[1,0,0]
	v_fma_mix_f32 v43, v24, s86, 0 op_sel:[1,0,0] op_sel_hi:[1,0,0]
	v_fma_mix_f32 v37, v25, s86, 0 op_sel_hi:[1,0,0]
	v_fma_mix_f32 v42, v25, s86, 0 op_sel:[1,0,0] op_sel_hi:[1,0,0]
	ds_read2_b64 v[24:27], v135 offset0:64 offset1:80
	v_exp_f32_e32 v36, v36
	v_exp_f32_e32 v43, v43
	v_exp_f32_e32 v37, v37
	v_exp_f32_e32 v42, v42
	v_add_f32_e32 v28, 1.0, v36
	v_add_f32_e32 v36, 1.0, v43
	v_rcp_f32_e32 v28, v28
	v_rcp_f32_e32 v29, v36
	s_waitcnt lgkmcnt(0)
	v_pk_mul_f16 v69, v67, v25
	v_add_f32_e32 v36, 1.0, v37
	v_add_f32_e32 v37, 1.0, v42
	v_rcp_f32_e32 v36, v36
	v_rcp_f32_e32 v37, v37
	v_pk_mul_f16 v68, v66, v24
	v_pk_fma_f32 v[24:25], v[28:29], -2.0, 1.0 op_sel_hi:[1,0,0]
	v_pk_add_f16 v39, v39, v35 neg_lo:[0,1] neg_hi:[0,1]
	v_pk_fma_f32 v[28:29], v[36:37], -2.0, 1.0 op_sel_hi:[1,0,0]
	v_pk_fma_f16 v31, v39, v31, v35
	v_cvt_pk_f16_f32 v29, v28, v29
	v_cvt_pk_f16_f32 v28, v24, v25
	v_pk_fma_f16 v30, v38, v30, v34
	ds_write_b64 v109, v[28:29] offset:56320
	v_pk_fma_f16 v23, v70, v23, v41
	v_pk_fma_f16 v22, v11, v22, v40
	ds_write_b64 v213, v[30:31]
	ds_write_b64 v214, v[22:23] offset:9216
	ds_read_b64 v[28:29], v215
	ds_read_b64 v[42:43], v138
	ds_read_b64 v[34:35], v216
	ds_read_b64 v[30:31], v217
	ds_read_b64 v[72:73], v218
	ds_read2_b64 v[22:25], v141 offset1:32
	ds_read_b64 v[74:75], v140
	ds_read_b64 v[38:39], v142
	ds_read_b64 v[76:77], v219
	ds_read_b64 v[78:79], v137
	s_waitcnt lgkmcnt(12)
	ds_read_b64 v[36:37], v220
	s_waitcnt lgkmcnt(7)
	v_pk_add_f16 v30, v30, v28 neg_lo:[0,1] neg_hi:[0,1]
	v_pk_add_f16 v31, v31, v29 neg_lo:[0,1] neg_hi:[0,1]
	s_waitcnt lgkmcnt(3)
	v_pk_fma_f16 v70, v30, v38, v28
	v_pk_fma_f16 v71, v31, v39, v29
	ds_read_b64 v[80:81], v139
	ds_read2_b64 v[38:41], v141 offset0:96 offset1:112
	s_waitcnt lgkmcnt(4)
	v_pk_add_f16 v82, v72, v76 neg_lo:[0,1] neg_hi:[0,1]
	v_pk_add_f16 v83, v73, v77 neg_lo:[0,1] neg_hi:[0,1]
	v_pk_add_f16 v84, v74, v42 neg_lo:[0,1] neg_hi:[0,1]
	s_waitcnt lgkmcnt(1)
	v_pk_add_f16 v85, v75, v43 neg_lo:[0,1] neg_hi:[0,1]
	v_pk_add_f16 v28, v80, v78 neg_lo:[0,1] neg_hi:[0,1]
	v_pk_add_f16 v29, v81, v79 neg_lo:[0,1] neg_hi:[0,1]
	s_waitcnt lgkmcnt(0)
	v_pk_fma_f16 v28, v28, v38, v78
	v_pk_fma_f16 v29, v29, v39, v79
	v_fma_mix_f32 v72, v28, s86, 0 op_sel_hi:[1,0,0]
	v_fma_mix_f32 v73, v28, s86, 0 op_sel:[1,0,0] op_sel_hi:[1,0,0]
	v_fma_mix_f32 v74, v29, s86, 0 op_sel_hi:[1,0,0]
	v_fma_mix_f32 v75, v29, s86, 0 op_sel:[1,0,0] op_sel_hi:[1,0,0]
	ds_read2_b64 v[28:31], v141 offset0:64 offset1:80
	v_exp_f32_e32 v72, v72
	v_exp_f32_e32 v73, v73
	v_exp_f32_e32 v74, v74
	v_exp_f32_e32 v75, v75
	v_add_f32_e32 v38, 1.0, v72
	v_add_f32_e32 v39, 1.0, v73
	v_add_f32_e32 v74, 1.0, v74
	v_add_f32_e32 v75, 1.0, v75
	v_rcp_f32_e32 v38, v38
	v_rcp_f32_e32 v39, v39
	v_rcp_f32_e32 v74, v74
	v_rcp_f32_e32 v75, v75
	v_mov_b32_e32 v11, v10
	s_waitcnt lgkmcnt(0)
	v_pk_mul_f16 v73, v71, v29
	v_pk_mul_f16 v72, v70, v28
	v_pk_fma_f32 v[28:29], v[38:39], -2.0, 1.0 op_sel_hi:[1,0,0]
	v_pk_fma_f32 v[38:39], v[74:75], -2.0, 1.0 op_sel_hi:[1,0,0]
	v_pk_fma_f16 v75, v83, v25, v77
	v_dot2c_f32_f16_e32 v11, v68, v68
	v_pk_fma_f16 v74, v82, v24, v76
	v_pk_fma_f16 v40, v84, v40, v42
	v_dot2c_f32_f16_e32 v11, v69, v69
	v_dot2c_f32_f16_e32 v11, v72, v72
	v_dot2c_f32_f16_e32 v11, v73, v73
	v_pk_fma_f16 v41, v85, v41, v43
	s_nop 1
	ds_bpermute_b32 v43, v221, v11
	v_cvt_pk_f16_f32 v25, v38, v39
	v_cvt_pk_f16_f32 v24, v28, v29
	ds_write_b64 v113, v[24:25] offset:56320
	s_waitcnt lgkmcnt(1)
	v_add_f32_e32 v11, v11, v43
	ds_bpermute_b32 v24, v222, v11
	ds_write_b64 v223, v[40:41]
	ds_write_b64 v224, v[74:75] offset:9216
	s_waitcnt lgkmcnt(2)
	s_and_saveexec_b64 s[22:23], s[0:1]
	s_cbranch_execz .LBB0_541
	s_waitcnt lgkmcnt(0)
	v_add_f32_e32 v11, v11, v24
	v_add_u32_e32 v24, s80, v97
	ds_write_b32 v24, v11

.LBB0_594:
	s_setprio 0
	s_cmpk_gt_u32 s96, 0xff
	s_cbranch_scc0 .Lsp2
	s_setprio 1
